# layer-0 input copy/convert loop: 4 elements per iteration with counted vmcnt
# baseline (speedup 1.0000x reference)
; DEVI int opaque_tid() { int t = __builtin_amdgcn_workitem_id_x(); asm volatile("" : "+v"(t)); return t; }
; DEVI void phase_prep(const Params& p, int L, char* smem) {
;     ...
;   if (L == 0) {
;     const long gt = (long)blockIdx.x * 256 + opaque_tid(), gn = (long)G * 256;
;     const f32x4* xs = (const f32x4*)p.in[0];
;     f32x4* xo = (f32x4*)p.out;
;     u32x2* xb = (u32x2*)(ws + OFF_XB);
;     for (long i = gt; i < (long)T_TOK * 1024 / 4; i += gn) {
;       f32x4 v = xs[i]; xo[i] = v;
;       xb[i] = u32x2{pack2(v[0], v[1]), pack2(v[2], v[3])};
;     }
.Lxc4:
	v_lshl_add_u64 v[232:233], v[10:11], 0, s[16:17]
	v_lshl_add_u64 v[232:233], v[232:233], 0, s[16:17]
	v_lshl_add_u64 v[232:233], v[232:233], 0, s[16:17]
	s_mov_b64 s[6:7], 0x7fffff
	v_cmp_ge_i64_e32 vcc, s[6:7], v[232:233]
	s_nop 1
	s_cmp_eq_u64 vcc, exec
	s_cbranch_scc0 .Lxc_rem
	v_lshl_add_u64 v[232:233], s[60:61], 0, v[6:7]
	v_lshl_add_u64 v[234:235], v[232:233], 0, s[18:19]
	global_load_dwordx4 v[236:239], v[232:233], off
	v_lshl_add_u64 v[232:233], v[234:235], 0, s[18:19]
	global_load_dwordx4 v[240:243], v[234:235], off
	v_lshl_add_u64 v[234:235], v[232:233], 0, s[18:19]
	global_load_dwordx4 v[244:247], v[232:233], off
	global_load_dwordx4 v[12:15], v[234:235], off
	v_lshl_add_u64 v[16:17], s[88:89], 0, v[6:7]
	s_waitcnt vmcnt(3)
	global_store_dwordx4 v[16:17], v[236:239], off
	v_lshl_add_u64 v[16:17], v[16:17], 0, s[18:19]
	s_nop 0
	v_cvt_pk_bf16_f32 v236, v236, v237
	v_cvt_pk_bf16_f32 v237, v238, v239
	global_store_dwordx2 v[8:9], v[236:237], off
	v_lshl_add_u64 v[8:9], v[8:9], 0, s[36:37]
	s_waitcnt vmcnt(4)
	global_store_dwordx4 v[16:17], v[240:243], off
	v_lshl_add_u64 v[16:17], v[16:17], 0, s[18:19]
	s_nop 0
	v_cvt_pk_bf16_f32 v240, v240, v241
	v_cvt_pk_bf16_f32 v241, v242, v243
	global_store_dwordx2 v[8:9], v[240:241], off
	v_lshl_add_u64 v[8:9], v[8:9], 0, s[36:37]
	s_waitcnt vmcnt(5)
	global_store_dwordx4 v[16:17], v[244:247], off
	v_lshl_add_u64 v[16:17], v[16:17], 0, s[18:19]
	s_nop 0
	v_cvt_pk_bf16_f32 v244, v244, v245
	v_cvt_pk_bf16_f32 v245, v246, v247
	global_store_dwordx2 v[8:9], v[244:245], off
	v_lshl_add_u64 v[8:9], v[8:9], 0, s[36:37]
	s_waitcnt vmcnt(6)
	global_store_dwordx4 v[16:17], v[12:15], off
	v_lshl_add_u64 v[16:17], v[16:17], 0, s[18:19]
	s_nop 0
	v_cvt_pk_bf16_f32 v12, v12, v13
	v_cvt_pk_bf16_f32 v13, v14, v15
	global_store_dwordx2 v[8:9], v[12:13], off
	v_lshl_add_u64 v[8:9], v[8:9], 0, s[36:37]
	v_lshl_add_u64 v[10:11], v[10:11], 0, s[16:17]
	v_lshl_add_u64 v[6:7], v[6:7], 0, s[18:19]
	v_lshl_add_u64 v[10:11], v[10:11], 0, s[16:17]
	v_lshl_add_u64 v[6:7], v[6:7], 0, s[18:19]
	v_lshl_add_u64 v[10:11], v[10:11], 0, s[16:17]
	v_lshl_add_u64 v[6:7], v[6:7], 0, s[18:19]
	v_lshl_add_u64 v[10:11], v[10:11], 0, s[16:17]
	v_lshl_add_u64 v[6:7], v[6:7], 0, s[18:19]
	s_branch .Lxc4
.Lxc_rem:
	s_mov_b64 s[6:7], 0x7fffff
	v_cmp_ge_i64_e32 vcc, s[6:7], v[10:11]
	s_nop 1
	s_and_b64 exec, exec, vcc
	s_cbranch_execz .LBB0_2193
